# LRU conv stage hand-rewritten: channel-pair packed FMA (64 v_pk_fma_f32 + 56 unpacks) instead of hipcc's tap-pair pk_mul + adds + shuffles (~230 fewer VALU per tile)
# speedup vs baseline: 1.0081x; 1.0026x over previous
; DI unsigned cvtpk(float lo, float hi) { unsigned r; asm volatile("v_cvt_pk_bf16_f32 %0, %1, %2" : "=v"(r) : "v"(lo), "v"(hi)); return r; }
; DI float bflo(unsigned w) { return __uint_as_float(w << 16); }
; DI float bfhi(unsigned w) { return __uint_as_float(w & 0xffff0000u); }
; DI void lru_tile(const Params& p, unsigned char* shm, int c, int nb, const LruPar par) {
;     ...
;         float xr[7][8];
; #pragma unroll
;         for (int k = 0; k < 7; ++k) { const int t = c * 128 + rg * 4 - 2 + k;
;             u32x4 v = {0u, 0u, 0u, 0u};
;             if (t >= 0 && t < S) v = *(const u32x4*)(ZU + (size_t)(nb >> 1) * S * 256 + (size_t)t * 256 + (nb & 1) * 128 + cgp * 8);
; #pragma unroll
;             for (int i = 0; i < 4; ++i) { xr[k][2 * i] = bflo(v[i]); xr[k][2 * i + 1] = bfhi(v[i]); } }
; #pragma unroll
;         for (int o = 0; o < 4; ++o) { float u8[8];
; #pragma unroll
;             for (int i = 0; i < 8; ++i) { float a = bias[i];
; #pragma unroll
;                 for (int tp = 0; tp < 4; ++tp) a += xr[o + tp][i] * w[tp][i];
;                 u8[i] = a; }
;             *(u32x4*)(UB + (rg * 4 + o) * LDU + cgp * 8) = (u32x4){cvtpk(u8[0], u8[1]), cvtpk(u8[2], u8[3]), cvtpk(u8[4], u8[5]), cvtpk(u8[6], u8[7])};
.Llru_rows_join:
	v_and_b32_e32 v240, 0x3c0, v202
	v_lshrrev_b32_e32 v240, 2, v240
	v_and_or_b32 v240, v202, 15, v240
	v_add_u32_e32 v240, s38, v240
	v_bfe_u32 v241, v202, 4, 2
	v_lshlrev_b32_e32 v240, 8, v240
	v_lshl_add_u32 v240, v241, 4, v240
	s_add_u32 s72, s34, 0x80000
	s_addc_u32 s73, s35, 0
	global_load_dwordx4 v[208:211], v240, s[34:35]
	global_load_dwordx4 v[216:219], v240, s[34:35] offset:64
	global_load_dwordx4 v[212:215], v240, s[72:73]
	global_load_dwordx4 v[220:223], v240, s[72:73] offset:64
	global_load_dwordx4 v[224:227], v240, s[34:35] offset:128
	global_load_dwordx4 v[232:235], v240, s[34:35] offset:192
	global_load_dwordx4 v[228:231], v240, s[72:73] offset:128
	global_load_dwordx4 v[236:239], v240, s[72:73] offset:192
	v_lshlrev_b32_e32 v96, 1, v98
	v_mad_u32_u24 v96, v95, s67, v96
	v_lshlrev_b32_e32 v100, 16, v40
	v_and_b32_e32 v101, 0xffff0000, v40
	v_lshlrev_b32_e32 v102, 16, v41
	v_and_b32_e32 v103, 0xffff0000, v41
	v_lshlrev_b32_e32 v104, 16, v42
	v_and_b32_e32 v105, 0xffff0000, v42
	v_lshlrev_b32_e32 v106, 16, v43
	v_and_b32_e32 v107, 0xffff0000, v43
	v_lshlrev_b32_e32 v108, 16, v44
	v_and_b32_e32 v109, 0xffff0000, v44
	v_lshlrev_b32_e32 v110, 16, v45
	v_and_b32_e32 v111, 0xffff0000, v45
	v_lshlrev_b32_e32 v112, 16, v46
	v_and_b32_e32 v113, 0xffff0000, v46
	v_lshlrev_b32_e32 v114, 16, v47
	v_and_b32_e32 v115, 0xffff0000, v47
	v_lshlrev_b32_e32 v116, 16, v48
	v_and_b32_e32 v117, 0xffff0000, v48
	v_lshlrev_b32_e32 v118, 16, v49
	v_and_b32_e32 v119, 0xffff0000, v49
	v_lshlrev_b32_e32 v120, 16, v50
	v_and_b32_e32 v121, 0xffff0000, v50
	v_lshlrev_b32_e32 v122, 16, v51
	v_and_b32_e32 v123, 0xffff0000, v51
	v_lshlrev_b32_e32 v124, 16, v52
	v_and_b32_e32 v125, 0xffff0000, v52
	v_lshlrev_b32_e32 v126, 16, v53
	v_and_b32_e32 v127, 0xffff0000, v53
	v_lshlrev_b32_e32 v128, 16, v54
	v_and_b32_e32 v129, 0xffff0000, v54
	v_lshlrev_b32_e32 v130, 16, v55
	v_and_b32_e32 v131, 0xffff0000, v55
	v_pk_fma_f32 v[132:133], v[100:101], v[36:37], v[20:21]
	v_pk_fma_f32 v[134:135], v[102:103], v[38:39], v[22:23]
	v_pk_fma_f32 v[136:137], v[104:105], v[28:29], v[8:9]
	v_pk_fma_f32 v[138:139], v[106:107], v[30:31], v[10:11]
	v_pk_fma_f32 v[132:133], v[108:109], v[12:13], v[132:133]
	v_pk_fma_f32 v[134:135], v[110:111], v[14:15], v[134:135]
	v_pk_fma_f32 v[136:137], v[112:113], v[0:1], v[136:137]
	v_pk_fma_f32 v[138:139], v[114:115], v[2:3], v[138:139]
	v_pk_fma_f32 v[132:133], v[116:117], v[32:33], v[132:133]
	v_pk_fma_f32 v[134:135], v[118:119], v[34:35], v[134:135]
	v_pk_fma_f32 v[136:137], v[120:121], v[24:25], v[136:137]
	v_pk_fma_f32 v[138:139], v[122:123], v[26:27], v[138:139]
	v_pk_fma_f32 v[132:133], v[124:125], v[16:17], v[132:133]
	v_pk_fma_f32 v[134:135], v[126:127], v[18:19], v[134:135]
	v_pk_fma_f32 v[136:137], v[128:129], v[4:5], v[136:137]
	v_pk_fma_f32 v[138:139], v[130:131], v[6:7], v[138:139]
	v_cvt_pk_bf16_f32 v140, v132, v133
	v_cvt_pk_bf16_f32 v141, v134, v135
	v_cvt_pk_bf16_f32 v142, v136, v137
	v_cvt_pk_bf16_f32 v143, v138, v139
	ds_write_b128 v96, v[140:143]
	v_lshlrev_b32_e32 v100, 16, v56
	v_and_b32_e32 v101, 0xffff0000, v56
	v_lshlrev_b32_e32 v102, 16, v57
	v_and_b32_e32 v103, 0xffff0000, v57
	v_lshlrev_b32_e32 v104, 16, v58
	v_and_b32_e32 v105, 0xffff0000, v58
	v_lshlrev_b32_e32 v106, 16, v59
	v_and_b32_e32 v107, 0xffff0000, v59
	v_pk_fma_f32 v[132:133], v[108:109], v[36:37], v[20:21]
	v_pk_fma_f32 v[134:135], v[110:111], v[38:39], v[22:23]
	v_pk_fma_f32 v[136:137], v[112:113], v[28:29], v[8:9]
	v_pk_fma_f32 v[138:139], v[114:115], v[30:31], v[10:11]
	v_pk_fma_f32 v[132:133], v[116:117], v[12:13], v[132:133]
	v_pk_fma_f32 v[134:135], v[118:119], v[14:15], v[134:135]
	v_pk_fma_f32 v[136:137], v[120:121], v[0:1], v[136:137]
	v_pk_fma_f32 v[138:139], v[122:123], v[2:3], v[138:139]
	v_pk_fma_f32 v[132:133], v[124:125], v[32:33], v[132:133]
	v_pk_fma_f32 v[134:135], v[126:127], v[34:35], v[134:135]
	v_pk_fma_f32 v[136:137], v[128:129], v[24:25], v[136:137]
	v_pk_fma_f32 v[138:139], v[130:131], v[26:27], v[138:139]
	v_pk_fma_f32 v[132:133], v[100:101], v[16:17], v[132:133]
	v_pk_fma_f32 v[134:135], v[102:103], v[18:19], v[134:135]
	v_pk_fma_f32 v[136:137], v[104:105], v[4:5], v[136:137]
	v_pk_fma_f32 v[138:139], v[106:107], v[6:7], v[138:139]
	v_cvt_pk_bf16_f32 v140, v132, v133
	v_cvt_pk_bf16_f32 v141, v134, v135
	v_cvt_pk_bf16_f32 v142, v136, v137
	v_cvt_pk_bf16_f32 v143, v138, v139
	ds_write_b128 v96, v[140:143] offset:272
	v_lshlrev_b32_e32 v108, 16, v60
	v_and_b32_e32 v109, 0xffff0000, v60
	v_lshlrev_b32_e32 v110, 16, v61
	v_and_b32_e32 v111, 0xffff0000, v61
	v_lshlrev_b32_e32 v112, 16, v62
	v_and_b32_e32 v113, 0xffff0000, v62
	v_lshlrev_b32_e32 v114, 16, v63
	v_and_b32_e32 v115, 0xffff0000, v63
	v_pk_fma_f32 v[132:133], v[116:117], v[36:37], v[20:21]
	v_pk_fma_f32 v[134:135], v[118:119], v[38:39], v[22:23]
	v_pk_fma_f32 v[136:137], v[120:121], v[28:29], v[8:9]
	v_pk_fma_f32 v[138:139], v[122:123], v[30:31], v[10:11]
	v_pk_fma_f32 v[132:133], v[124:125], v[12:13], v[132:133]
	v_pk_fma_f32 v[134:135], v[126:127], v[14:15], v[134:135]
	v_pk_fma_f32 v[136:137], v[128:129], v[0:1], v[136:137]
	v_pk_fma_f32 v[138:139], v[130:131], v[2:3], v[138:139]
	v_pk_fma_f32 v[132:133], v[100:101], v[32:33], v[132:133]
	v_pk_fma_f32 v[134:135], v[102:103], v[34:35], v[134:135]
	v_pk_fma_f32 v[136:137], v[104:105], v[24:25], v[136:137]
	v_pk_fma_f32 v[138:139], v[106:107], v[26:27], v[138:139]
	v_pk_fma_f32 v[132:133], v[108:109], v[16:17], v[132:133]
	v_pk_fma_f32 v[134:135], v[110:111], v[18:19], v[134:135]
	v_pk_fma_f32 v[136:137], v[112:113], v[4:5], v[136:137]
	v_pk_fma_f32 v[138:139], v[114:115], v[6:7], v[138:139]
; DI unsigned cvtpk(float lo, float hi) { unsigned r; asm volatile("v_cvt_pk_bf16_f32 %0, %1, %2" : "=v"(r) : "v"(lo), "v"(hi)); return r; }
; DI void lru_tile(const Params& p, unsigned char* shm, int c, int nb, const LruPar par) {
;     ...
;         for (int o = 0; o < 4; ++o) { float u8[8];
; #pragma unroll
;             for (int i = 0; i < 8; ++i) { float a = bias[i];
; #pragma unroll
;                 for (int tp = 0; tp < 4; ++tp) a += xr[o + tp][i] * w[tp][i];
;                 u8[i] = a; }
;             *(u32x4*)(UB + (rg * 4 + o) * LDU + cgp * 8) = (u32x4){cvtpk(u8[0], u8[1]), cvtpk(u8[2], u8[3]), cvtpk(u8[4], u8[5]), cvtpk(u8[6], u8[7])};
;         }
;     }
;     __syncthreads();
;     ...
;         bf16x8 bfr[4][2];
; #pragma unroll
;         for (int s = 0; s < 4; ++s)
; #pragma unroll
;             for (int gt = 0; gt < 2; ++gt) bfr[s][gt] = *(const bf16x8*)(LWT + ((size_t)((d * 2 + gt) * 16 + nb) * 128 + chl) * 128 + s * 32 + q * 8);
; #pragma unroll
;         for (int s = 0; s < 4; ++s) {
; #pragma unroll
;             for (int rt = 0; rt < 8; ++rt) {
;                 const bf16x8 af = *(const bf16x8*)(UB + (rt * 16 + col) * LDU + s * 32 + q * 8);
; #pragma unroll
;                 for (int gt = 0; gt < 2; ++gt) acc[gt][rt] = __builtin_amdgcn_mfma_f32_16x16x32_bf16(af, bfr[s][gt], acc[gt][rt], 0, 0, 0);
	v_cvt_pk_bf16_f32 v140, v132, v133
	v_cvt_pk_bf16_f32 v141, v134, v135
	v_cvt_pk_bf16_f32 v142, v136, v137
	v_cvt_pk_bf16_f32 v143, v138, v139
	ds_write_b128 v96, v[140:143] offset:544
	v_lshlrev_b32_e32 v116, 16, v64
	v_and_b32_e32 v117, 0xffff0000, v64
	v_lshlrev_b32_e32 v118, 16, v65
	v_and_b32_e32 v119, 0xffff0000, v65
	v_lshlrev_b32_e32 v120, 16, v66
	v_and_b32_e32 v121, 0xffff0000, v66
	v_lshlrev_b32_e32 v122, 16, v67
	v_and_b32_e32 v123, 0xffff0000, v67
	v_pk_fma_f32 v[132:133], v[124:125], v[36:37], v[20:21]
	v_pk_fma_f32 v[134:135], v[126:127], v[38:39], v[22:23]
	v_pk_fma_f32 v[136:137], v[128:129], v[28:29], v[8:9]
	v_pk_fma_f32 v[138:139], v[130:131], v[30:31], v[10:11]
	v_pk_fma_f32 v[132:133], v[100:101], v[12:13], v[132:133]
	v_pk_fma_f32 v[134:135], v[102:103], v[14:15], v[134:135]
	v_pk_fma_f32 v[136:137], v[104:105], v[0:1], v[136:137]
	v_pk_fma_f32 v[138:139], v[106:107], v[2:3], v[138:139]
	v_pk_fma_f32 v[132:133], v[108:109], v[32:33], v[132:133]
	v_pk_fma_f32 v[134:135], v[110:111], v[34:35], v[134:135]
	v_pk_fma_f32 v[136:137], v[112:113], v[24:25], v[136:137]
	v_pk_fma_f32 v[138:139], v[114:115], v[26:27], v[138:139]
	v_pk_fma_f32 v[132:133], v[116:117], v[16:17], v[132:133]
	v_pk_fma_f32 v[134:135], v[118:119], v[18:19], v[134:135]
	v_pk_fma_f32 v[136:137], v[120:121], v[4:5], v[136:137]
	v_pk_fma_f32 v[138:139], v[122:123], v[6:7], v[138:139]
	v_cvt_pk_bf16_f32 v140, v132, v133
	v_cvt_pk_bf16_f32 v141, v134, v135
	v_cvt_pk_bf16_f32 v142, v136, v137
	v_cvt_pk_bf16_f32 v143, v138, v139
	ds_write_b128 v96, v[140:143] offset:816
	s_ashr_i32 s4, s6, 6
	v_and_b32_e32 v164, 15, v75
	v_lshl_or_b32 v48, s4, 4, v164
	s_lshl_b32 s4, s4, 12
	s_ashr_i32 s59, s58, 31
	s_add_i32 s8, s4, 0
	s_lshl_b64 s[4:5], s[58:59], 14
	v_bfe_u32 v99, v75, 4, 2
	v_ashrrev_i32_e32 v49, 31, v48
	s_add_u32 s4, s37, s4
	s_addc_u32 s5, s41, s5
	v_lshlrev_b32_e32 v68, 4, v99
	v_lshl_add_u64 v[160:161], s[34:35], 0, v[68:69]
	v_add_u32_e32 v165, 0, v68
	s_waitcnt lgkmcnt(0)
	s_barrier
	v_mad_u32_u24 v68, v164, s67, v165
	v_lshl_add_u64 v[96:97], v[160:161], 0, v[8:9]
	ds_read_b128 v[4:7], v68
	ds_read_b128 v[12:15], v68 offset:4352
	ds_read_b128 v[32:35], v68 offset:8704
	ds_read_b128 v[36:39], v68 offset:13056
	ds_read_b128 v[50:53], v68 offset:17408
	ds_read_b128 v[54:57], v68 offset:21760
	ds_read_b128 v[58:61], v68 offset:26112
	ds_read_b128 v[116:119], v68 offset:30464
	s_waitcnt vmcnt(7) lgkmcnt(7)
	v_mfma_f32_16x16x32_bf16 v[16:19], v[4:7], v[208:211], 0
	v_cmp_eq_u32_e64 s[10:11], 0, v99
	s_waitcnt lgkmcnt(6)
	v_mfma_f32_16x16x32_bf16 v[28:31], v[12:15], v[208:211], 0
	s_waitcnt lgkmcnt(5)
	v_mfma_f32_16x16x32_bf16 v[40:43], v[32:35], v[208:211], 0
	s_waitcnt lgkmcnt(4)
	v_mfma_f32_16x16x32_bf16 v[44:47], v[36:39], v[208:211], 0
	s_waitcnt lgkmcnt(3)
	v_mfma_f32_16x16x32_bf16 v[62:65], v[50:53], v[208:211], 0
	s_waitcnt vmcnt(5)
	v_mfma_f32_16x16x32_bf16 v[50:53], v[50:53], v[212:215], 0
	s_waitcnt lgkmcnt(2)
	v_mfma_f32_16x16x32_bf16 v[100:103], v[54:57], v[208:211], 0
	v_mfma_f32_16x16x32_bf16 v[104:107], v[54:57], v[212:215], 0
	v_lshl_add_u32 v55, v164, 3, s8
	v_add_u32_e32 v54, s38, v48
	s_waitcnt lgkmcnt(1)
	v_mfma_f32_16x16x32_bf16 v[120:123], v[58:61], v[208:211], 0
	v_mfma_f32_16x16x32_bf16 v[132:135], v[58:61], v[212:215], 0
	v_add_u32_e32 v59, 0x19800, v55
	v_ashrrev_i32_e32 v55, 31, v54
	v_lshlrev_b32_e32 v58, 1, v48
	s_waitcnt lgkmcnt(0)
	v_mfma_f32_16x16x32_bf16 v[0:3], v[116:119], v[208:211], 0
	v_lshl_add_u32 v61, v99, 7, v59
	v_lshl_add_u64 v[56:57], v[54:55], 3, s[4:5]
	v_mfma_f32_16x16x32_bf16 v[4:7], v[4:7], v[212:215], 0
	v_mfma_f32_16x16x32_bf16 v[12:15], v[12:15], v[212:215], 0
	v_mfma_f32_16x16x32_bf16 v[32:35], v[32:35], v[212:215], 0
	v_mfma_f32_16x16x32_bf16 v[36:39], v[36:39], v[212:215], 0
	v_mfma_f32_16x16x32_bf16 v[20:23], v[116:119], v[212:215], 0
	ds_read_b128 v[116:119], v68 offset:64
	ds_read_b128 v[136:139], v68 offset:4416
	s_waitcnt lgkmcnt(1)
	v_mfma_f32_16x16x32_bf16 v[16:19], v[116:119], v[216:219], v[16:19]
	s_waitcnt vmcnt(4)
	v_mfma_f32_16x16x32_bf16 v[4:7], v[116:119], v[220:223], v[4:7]
	s_waitcnt lgkmcnt(0)
	v_mfma_f32_16x16x32_bf16 v[28:31], v[136:139], v[216:219], v[28:31]
	v_mfma_f32_16x16x32_bf16 v[12:15], v[136:139], v[220:223], v[12:15]
	ds_read_b128 v[116:119], v68 offset:8768
	ds_read_b128 v[136:139], v68 offset:13120
	s_waitcnt lgkmcnt(1)
	v_mfma_f32_16x16x32_bf16 v[40:43], v[116:119], v[216:219], v[40:43]
	v_mfma_f32_16x16x32_bf16 v[32:35], v[116:119], v[220:223], v[32:35]
	s_waitcnt lgkmcnt(0)
	v_mfma_f32_16x16x32_bf16 v[44:47], v[136:139], v[216:219], v[44:47]
	v_mfma_f32_16x16x32_bf16 v[36:39], v[136:139], v[220:223], v[36:39]
	ds_read_b128 v[116:119], v68 offset:17472
	ds_read_b128 v[136:139], v68 offset:21824
	s_waitcnt lgkmcnt(1)
	v_mfma_f32_16x16x32_bf16 v[62:65], v[116:119], v[216:219], v[62:65]
	v_mfma_f32_16x16x32_bf16 v[50:53], v[116:119], v[220:223], v[50:53]
	s_waitcnt lgkmcnt(0)
	v_mfma_f32_16x16x32_bf16 v[100:103], v[136:139], v[216:219], v[100:103]
	v_mfma_f32_16x16x32_bf16 v[104:107], v[136:139], v[220:223], v[104:107]
	ds_read_b128 v[116:119], v68 offset:26176
	ds_read_b128 v[136:139], v68 offset:30528
	s_waitcnt lgkmcnt(1)
	v_mfma_f32_16x16x32_bf16 v[120:123], v[116:119], v[216:219], v[120:123]
	v_mfma_f32_16x16x32_bf16 v[116:119], v[116:119], v[220:223], v[132:135]
	s_waitcnt lgkmcnt(0)
	v_mfma_f32_16x16x32_bf16 v[0:3], v[136:139], v[216:219], v[0:3]
	v_mfma_f32_16x16x32_bf16 v[8:11], v[136:139], v[220:223], v[20:23]
	s_nop 2
	ds_read_b128 v[20:23], v68 offset:128
	ds_read_b128 v[24:27], v68 offset:4480
	s_waitcnt vmcnt(3) lgkmcnt(1)
; DI float bf2f(unsigned short b) { return __uint_as_float(((unsigned)b) << 16); }
; DI float ex2(float x) { return __builtin_amdgcn_exp2f(x); }
; DI float rcpf_(float x) { return __builtin_amdgcn_rcpf(x); }
; DI void lru_tile(const Params& p, unsigned char* shm, int c, int nb, const LruPar par) {
;     ...
;         for (int s = 0; s < 4; ++s) {
; #pragma unroll
;             for (int rt = 0; rt < 8; ++rt) {
;                 const bf16x8 af = *(const bf16x8*)(UB + (rt * 16 + col) * LDU + s * 32 + q * 8);
; #pragma unroll
;                 for (int gt = 0; gt < 2; ++gt) acc[gt][rt] = __builtin_amdgcn_mfma_f32_16x16x32_bf16(af, bfr[s][gt], acc[gt][rt], 0, 0, 0);
;             }
;             __builtin_amdgcn_sched_barrier(0);
;         }
;         const f32x2 nl2 = {-LOG2E, -LOG2E}, nbr2 = {par.nbr[d], par.nbr[d]}, nbi2 = {par.nbi[d], par.nbi[d]}, cd2 = {par.cdec[d], par.cdec[d]}, one2 = {1.f, 1.f};
;         float hl[8][4], pc[8][4];
; #pragma unroll
;         for (int rt = 0; rt < 8; ++rt) {
;             float av[4], bv[4];
; #pragma unroll
;             for (int jp = 0; jp < 2; ++jp) {
;                 const f32x2 xr = {acc[0][rt][2 * jp], acc[0][rt][2 * jp + 1]}, xi = {acc[1][rt][2 * jp], acc[1][rt][2 * jp + 1]};
;                 f32x2 er = xr * nl2 + nbr2, ei = xi * nl2 + nbi2;
;                 er = (f32x2){ex2(er[0]), ex2(er[1])} + one2; ei = (f32x2){ex2(ei[0]), ex2(ei[1])} + one2;
;                 const f32x2 r = {rcpf_(er[0]), rcpf_(er[1])}, ig = {rcpf_(ei[0]), rcpf_(ei[1])};
;                 const f32x2 la = r * cd2;
;                 const f32x2 a = {ex2(la[0]), ex2(la[1])};
;                 const f32x2 om = one2 - a * a;
;                 const f32x2 sc = {__builtin_amdgcn_sqrtf(om[0]), __builtin_amdgcn_sqrtf(om[1])};
;                 const f32x2 u2 = {bf2f(UB[(rt * 16 + 4 * q + 2 * jp) * LDU + chl]), bf2f(UB[(rt * 16 + 4 * q + 2 * jp + 1) * LDU + chl])};
;                 const f32x2 b2 = sc * ig * u2;
;                 av[2 * jp] = a[0]; av[2 * jp + 1] = a[1]; bv[2 * jp] = b2[0]; bv[2 * jp + 1] = b2[1];
	v_mfma_f32_16x16x32_bf16 v[16:19], v[20:23], v[224:227], v[16:19]
	s_waitcnt vmcnt(1)
	v_mfma_f32_16x16x32_bf16 v[4:7], v[20:23], v[228:231], v[4:7]
	s_waitcnt lgkmcnt(0)
	v_mfma_f32_16x16x32_bf16 v[20:23], v[24:27], v[224:227], v[28:31]
	v_mfma_f32_16x16x32_bf16 v[12:15], v[24:27], v[228:231], v[12:15]
	ds_read_b128 v[24:27], v68 offset:8832
	s_nop 0
	ds_read_b128 v[28:31], v68 offset:13184
	s_waitcnt lgkmcnt(1)
	v_mfma_f32_16x16x32_bf16 v[40:43], v[24:27], v[224:227], v[40:43]
	v_mfma_f32_16x16x32_bf16 v[24:27], v[24:27], v[228:231], v[32:35]
	s_waitcnt lgkmcnt(0)
	v_mfma_f32_16x16x32_bf16 v[32:35], v[28:31], v[224:227], v[44:47]
	v_mfma_f32_16x16x32_bf16 v[28:31], v[28:31], v[228:231], v[36:39]
	s_nop 2
	ds_read_b128 v[36:39], v68 offset:17536
	ds_read_b128 v[44:47], v68 offset:21888
	s_waitcnt lgkmcnt(1)
	v_mfma_f32_16x16x32_bf16 v[62:65], v[36:39], v[224:227], v[62:65]
	v_mfma_f32_16x16x32_bf16 v[50:53], v[36:39], v[228:231], v[50:53]
	s_waitcnt lgkmcnt(0)
	v_mfma_f32_16x16x32_bf16 v[100:103], v[44:47], v[224:227], v[100:103]
	v_mfma_f32_16x16x32_bf16 v[104:107], v[44:47], v[228:231], v[104:107]
	ds_read_b128 v[36:39], v68 offset:26240
	ds_read_b128 v[44:47], v68 offset:30592
	s_waitcnt lgkmcnt(1)
	v_mfma_f32_16x16x32_bf16 v[120:123], v[36:39], v[224:227], v[120:123]
	v_mfma_f32_16x16x32_bf16 v[116:119], v[36:39], v[228:231], v[116:119]
	s_waitcnt lgkmcnt(0)
	v_mfma_f32_16x16x32_bf16 v[0:3], v[44:47], v[224:227], v[0:3]
	v_mfma_f32_16x16x32_bf16 v[108:111], v[44:47], v[228:231], v[8:11]
	s_nop 2
	ds_read_b128 v[8:11], v68 offset:192
	ds_read_b128 v[36:39], v68 offset:4544
	s_waitcnt lgkmcnt(1)
	v_mfma_f32_16x16x32_bf16 v[124:127], v[8:11], v[232:235], v[16:19]
	s_waitcnt vmcnt(0)
	v_mfma_f32_16x16x32_bf16 v[132:135], v[8:11], v[236:239], v[4:7]
	s_nop 2
	ds_read_b128 v[4:7], v68 offset:8896
	ds_read_b128 v[8:11], v68 offset:13248
	s_waitcnt lgkmcnt(2)
	v_mfma_f32_16x16x32_bf16 v[136:139], v[36:39], v[232:235], v[20:23]
	v_mfma_f32_16x16x32_bf16 v[140:143], v[36:39], v[236:239], v[12:15]
	s_waitcnt lgkmcnt(1)
	v_mfma_f32_16x16x32_bf16 v[44:47], v[4:7], v[232:235], v[40:43]
	v_mfma_f32_16x16x32_bf16 v[40:43], v[4:7], v[236:239], v[24:27]
	s_waitcnt lgkmcnt(0)
	v_mfma_f32_16x16x32_bf16 v[36:39], v[8:11], v[232:235], v[32:35]
	v_mfma_f32_16x16x32_bf16 v[32:35], v[8:11], v[236:239], v[28:31]
	ds_read_b128 v[4:7], v68 offset:17600
	ds_read_b128 v[8:11], v68 offset:21952
	s_waitcnt lgkmcnt(1)
	v_mfma_f32_16x16x32_bf16 v[28:31], v[4:7], v[232:235], v[62:65]
	v_mfma_f32_16x16x32_bf16 v[24:27], v[4:7], v[236:239], v[50:53]
	ds_read_b128 v[4:7], v68 offset:26304
	s_nop 1
	ds_read_b128 v[50:53], v68 offset:30656
	s_waitcnt lgkmcnt(2)
	v_mfma_f32_16x16x32_bf16 v[20:23], v[8:11], v[232:235], v[100:103]
	v_mfma_f32_16x16x32_bf16 v[16:19], v[8:11], v[236:239], v[104:107]
	s_waitcnt lgkmcnt(1)
	v_mfma_f32_16x16x32_bf16 v[12:15], v[4:7], v[232:235], v[120:123]
	v_mfma_f32_16x16x32_bf16 v[8:11], v[4:7], v[236:239], v[116:119]
	s_waitcnt lgkmcnt(0)
	v_mfma_f32_16x16x32_bf16 v[4:7], v[50:53], v[232:235], v[0:3]
	v_mfma_f32_16x16x32_bf16 v[0:3], v[50:53], v[236:239], v[108:111]
	s_add_u32 s74, s34, 0x100000
	s_addc_u32 s75, s35, 0
	s_add_u32 s76, s34, 0x180000
	s_addc_u32 s77, s35, 0
	global_load_dwordx4 v[208:211], v240, s[74:75]
	global_load_dwordx4 v[216:219], v240, s[74:75] offset:64
	global_load_dwordx4 v[212:215], v240, s[76:77]
	global_load_dwordx4 v[220:223], v240, s[76:77] offset:64
	global_load_dwordx4 v[224:227], v240, s[74:75] offset:128
	global_load_dwordx4 v[228:231], v240, s[74:75] offset:192
	global_load_dwordx4 v[232:235], v240, s[76:77] offset:128
	global_load_dwordx4 v[236:239], v240, s[76:77] offset:192
	v_fma_f32 v52, -v126, s50, v82
	v_fma_f32 v53, -v127, s50, v82
	v_pk_fma_f32 v[54:55], v[134:135], s[50:51], v[86:87] op_sel_hi:[1,0,0] neg_lo:[1,0,0] neg_hi:[1,0,0]
	v_exp_f32_e32 v52, v52
	v_exp_f32_e32 v53, v53
	v_pk_fma_f32 v[50:51], v[124:125], s[50:51], v[82:83] op_sel_hi:[1,0,0] neg_lo:[1,0,0] neg_hi:[1,0,0]
	v_exp_f32_e32 v54, v54
	v_exp_f32_e32 v55, v55
	v_pk_add_f32 v[52:53], v[52:53], 1.0 op_sel_hi:[1,0]
	v_exp_f32_e32 v50, v50
	v_rcp_f32_e32 v52, v52
	v_rcp_f32_e32 v53, v53
	v_exp_f32_e32 v51, v51
	v_mul_u32_u24_e32 v95, 0x220, v99
	v_lshlrev_b32_e32 v60, 1, v95
	v_pk_mul_f32 v[52:53], v[92:93], v[52:53] op_sel_hi:[0,1]
	v_exp_f32_e32 v62, v52
	v_exp_f32_e32 v63, v53
	v_pk_add_f32 v[52:53], v[54:55], 1.0 op_sel_hi:[1,0]
	v_pk_add_f32 v[50:51], v[50:51], 1.0 op_sel_hi:[1,0]
	v_rcp_f32_e32 v52, v52
	v_pk_fma_f32 v[54:55], v[62:63], v[62:63], 1.0 op_sel_hi:[1,1,0] neg_lo:[1,0,0] neg_hi:[1,0,0]
	v_rcp_f32_e32 v53, v53
	v_sqrt_f32_e32 v54, v54
	v_sqrt_f32_e32 v55, v55
	v_rcp_f32_e32 v50, v50
	v_rcp_f32_e32 v51, v51
	v_add3_u32 v68, 0, v58, v60
	v_pk_mul_f32 v[52:53], v[52:53], v[54:55]
	v_pk_fma_f32 v[54:55], v[132:133], s[50:51], v[86:87] op_sel_hi:[1,0,0] neg_lo:[1,0,0] neg_hi:[1,0,0]
	v_pk_mul_f32 v[50:51], v[92:93], v[50:51] op_sel_hi:[0,1]
	v_exp_f32_e32 v54, v54
	v_exp_f32_e32 v55, v55
	v_exp_f32_e32 v50, v50
	v_exp_f32_e32 v51, v51
	v_add3_u32 v97, 0, v60, v58
	ds_read_u16 v58, v68 offset:544
	ds_read_u16 v60, v97 offset:816
	v_pk_add_f32 v[54:55], v[54:55], 1.0 op_sel_hi:[1,0]
	ds_read_u16 v96, v97 offset:272
	ds_read_u16 v98, v68
	v_rcp_f32_e32 v64, v54
	v_rcp_f32_e32 v65, v55
	v_pk_fma_f32 v[54:55], v[50:51], v[50:51], 1.0 op_sel_hi:[1,1,0] neg_lo:[1,0,0] neg_hi:[1,0,0]
	s_nop 0
	v_sqrt_f32_e32 v66, v54
	v_sqrt_f32_e32 v67, v55
	s_waitcnt lgkmcnt(3)
	v_lshlrev_b32_e32 v54, 16, v58
	s_waitcnt lgkmcnt(2)
	v_lshlrev_b32_e32 v55, 16, v60
	v_pk_mul_f32 v[54:55], v[52:53], v[54:55]
	v_pk_mul_f32 v[52:53], v[64:65], v[66:67]
	s_waitcnt lgkmcnt(0)
; DI float bf2f(unsigned short b) { return __uint_as_float(((unsigned)b) << 16); }
; DI float ex2(float x) { return __builtin_amdgcn_exp2f(x); }
; DI float rcpf_(float x) { return __builtin_amdgcn_rcpf(x); }
; DI void lru_tile(const Params& p, unsigned char* shm, int c, int nb, const LruPar par) {
;     ...
;         for (int rt = 0; rt < 8; ++rt) {
;             float av[4], bv[4];
; #pragma unroll
;             for (int jp = 0; jp < 2; ++jp) {
;                 const f32x2 xr = {acc[0][rt][2 * jp], acc[0][rt][2 * jp + 1]}, xi = {acc[1][rt][2 * jp], acc[1][rt][2 * jp + 1]};
;                 f32x2 er = xr * nl2 + nbr2, ei = xi * nl2 + nbi2;
;                 er = (f32x2){ex2(er[0]), ex2(er[1])} + one2; ei = (f32x2){ex2(ei[0]), ex2(ei[1])} + one2;
;                 const f32x2 r = {rcpf_(er[0]), rcpf_(er[1])}, ig = {rcpf_(ei[0]), rcpf_(ei[1])};
;                 const f32x2 la = r * cd2;
;                 const f32x2 a = {ex2(la[0]), ex2(la[1])};
;                 const f32x2 om = one2 - a * a;
;                 const f32x2 sc = {__builtin_amdgcn_sqrtf(om[0]), __builtin_amdgcn_sqrtf(om[1])};
;                 const f32x2 u2 = {bf2f(UB[(rt * 16 + 4 * q + 2 * jp) * LDU + chl]), bf2f(UB[(rt * 16 + 4 * q + 2 * jp + 1) * LDU + chl])};
;                 const f32x2 b2 = sc * ig * u2;
;                 av[2 * jp] = a[0]; av[2 * jp + 1] = a[1]; bv[2 * jp] = b2[0]; bv[2 * jp + 1] = b2[1];
;             }
;             float h = 0.f, P = 1.f;
;             if (d == 0) {
; #pragma unroll
;                 for (int j = 0; j < 4; ++j) { h = fmaf(av[j], h, bv[j]); P *= av[j]; hl[rt][j] = h; pc[rt][j] = P; }
;             } else {
; #pragma unroll
;                 for (int j = 3; j >= 0; --j) { h = fmaf(av[j], h, bv[j]); P *= av[j]; hl[rt][j] = h; pc[rt][j] = P; }
;             }
;             AG[(rt * 4 + q) * 16 + col] = (f32x2){P, h};
;             __builtin_amdgcn_sched_barrier(0);
	v_lshlrev_b32_e32 v64, 16, v98
	v_lshlrev_b32_e32 v65, 16, v96
	v_pk_mul_f32 v[52:53], v[52:53], v[64:65]
	s_nop 0
	v_fma_f32 v52, 0, v50, v52
	v_fmac_f32_e32 v53, v51, v52
	v_mul_f32_e32 v51, v50, v51
	v_fma_f32 v58, v62, v53, v54
	v_mul_f32_e32 v60, v62, v51
	v_fmac_f32_e32 v55, v63, v58
	v_mul_f32_e32 v54, v63, v60
	ds_write_b64 v61, v[54:55]
	v_pk_fma_f32 v[64:65], v[138:139], s[50:51], v[82:83] op_sel_hi:[1,0,0] neg_lo:[1,0,0] neg_hi:[1,0,0]
	v_pk_fma_f32 v[66:67], v[142:143], s[50:51], v[86:87] op_sel_hi:[1,0,0] neg_lo:[1,0,0] neg_hi:[1,0,0]
	v_exp_f32_e32 v64, v64
	v_exp_f32_e32 v65, v65
	v_pk_fma_f32 v[62:63], v[136:137], s[50:51], v[82:83] op_sel_hi:[1,0,0] neg_lo:[1,0,0] neg_hi:[1,0,0]
	v_exp_f32_e32 v66, v66
	v_exp_f32_e32 v67, v67
	v_pk_add_f32 v[64:65], v[64:65], 1.0 op_sel_hi:[1,0]
	v_exp_f32_e32 v62, v62
	v_rcp_f32_e32 v64, v64
	v_rcp_f32_e32 v65, v65
	v_exp_f32_e32 v63, v63
	ds_read_u16 v96, v68 offset:4896
	ds_read_u16 v98, v97 offset:5168
	ds_read_u16 v106, v97 offset:4624
	ds_read_u16 v107, v68 offset:4352
	v_pk_mul_f32 v[64:65], v[92:93], v[64:65] op_sel_hi:[0,1]
	v_exp_f32_e32 v100, v64
	v_exp_f32_e32 v101, v65
	v_pk_add_f32 v[64:65], v[66:67], 1.0 op_sel_hi:[1,0]
	v_pk_add_f32 v[62:63], v[62:63], 1.0 op_sel_hi:[1,0]
	v_rcp_f32_e32 v64, v64
	v_pk_fma_f32 v[66:67], v[100:101], v[100:101], 1.0 op_sel_hi:[1,1,0] neg_lo:[1,0,0] neg_hi:[1,0,0]
	v_rcp_f32_e32 v65, v65
	v_sqrt_f32_e32 v66, v66
	v_sqrt_f32_e32 v67, v67
	v_rcp_f32_e32 v62, v62
	v_rcp_f32_e32 v63, v63
	v_pk_mul_f32 v[64:65], v[64:65], v[66:67]
	v_pk_fma_f32 v[66:67], v[140:141], s[50:51], v[86:87] op_sel_hi:[1,0,0] neg_lo:[1,0,0] neg_hi:[1,0,0]
	v_pk_mul_f32 v[62:63], v[92:93], v[62:63] op_sel_hi:[0,1]
	v_exp_f32_e32 v66, v66
	v_exp_f32_e32 v67, v67
	v_exp_f32_e32 v62, v62
	v_exp_f32_e32 v63, v63
	v_pk_add_f32 v[66:67], v[66:67], 1.0 op_sel_hi:[1,0]
	s_nop 0
	v_rcp_f32_e32 v102, v66
	v_rcp_f32_e32 v103, v67
	v_pk_fma_f32 v[66:67], v[62:63], v[62:63], 1.0 op_sel_hi:[1,1,0] neg_lo:[1,0,0] neg_hi:[1,0,0]
	s_nop 0
	v_sqrt_f32_e32 v104, v66
	v_sqrt_f32_e32 v105, v67
	s_waitcnt lgkmcnt(3)
	v_lshlrev_b32_e32 v66, 16, v96
	s_waitcnt lgkmcnt(2)
	v_lshlrev_b32_e32 v67, 16, v98
	v_pk_mul_f32 v[66:67], v[64:65], v[66:67]
	v_pk_mul_f32 v[64:65], v[102:103], v[104:105]
	s_waitcnt lgkmcnt(0)
	v_lshlrev_b32_e32 v102, 16, v107
	v_lshlrev_b32_e32 v103, 16, v106
	v_pk_mul_f32 v[64:65], v[64:65], v[102:103]
	s_nop 0
	v_fma_f32 v64, 0, v62, v64
	v_fmac_f32_e32 v65, v63, v64
	v_mul_f32_e32 v63, v62, v63
	v_fma_f32 v96, v100, v65, v66
	v_mul_f32_e32 v98, v100, v63
	v_fmac_f32_e32 v67, v101, v96
	v_mul_f32_e32 v66, v101, v98
	ds_write_b64 v61, v[66:67] offset:512
	v_pk_fma_f32 v[46:47], v[46:47], s[50:51], v[82:83] op_sel_hi:[1,0,0] neg_lo:[1,0,0] neg_hi:[1,0,0]
	v_pk_fma_f32 v[44:45], v[44:45], s[50:51], v[82:83] op_sel_hi:[1,0,0] neg_lo:[1,0,0] neg_hi:[1,0,0]
	v_exp_f32_e32 v46, v46
	v_exp_f32_e32 v47, v47
	v_exp_f32_e32 v44, v44
	v_exp_f32_e32 v45, v45
	v_pk_fma_f32 v[42:43], v[42:43], s[50:51], v[86:87] op_sel_hi:[1,0,0] neg_lo:[1,0,0] neg_hi:[1,0,0]
	v_pk_add_f32 v[46:47], v[46:47], 1.0 op_sel_hi:[1,0]
	v_exp_f32_e32 v42, v42
	v_rcp_f32_e32 v46, v46
	v_rcp_f32_e32 v47, v47
	v_pk_add_f32 v[44:45], v[44:45], 1.0 op_sel_hi:[1,0]
	v_exp_f32_e32 v43, v43
	v_rcp_f32_e32 v44, v44
	v_pk_mul_f32 v[46:47], v[92:93], v[46:47] op_sel_hi:[0,1]
	v_exp_f32_e32 v46, v46
	v_exp_f32_e32 v47, v47
	v_rcp_f32_e32 v45, v45
	v_pk_add_f32 v[42:43], v[42:43], 1.0 op_sel_hi:[1,0]
	v_pk_fma_f32 v[40:41], v[40:41], s[50:51], v[86:87] op_sel_hi:[1,0,0] neg_lo:[1,0,0] neg_hi:[1,0,0]
	v_pk_fma_f32 v[100:101], v[46:47], v[46:47], 1.0 op_sel_hi:[1,1,0] neg_lo:[1,0,0] neg_hi:[1,0,0]
	v_rcp_f32_e32 v42, v42
	v_rcp_f32_e32 v43, v43
	v_sqrt_f32_e32 v102, v100
	v_sqrt_f32_e32 v103, v101
	v_pk_mul_f32 v[44:45], v[92:93], v[44:45] op_sel_hi:[0,1]
	v_exp_f32_e32 v100, v44
	v_exp_f32_e32 v40, v40
	v_exp_f32_e32 v41, v41
	v_exp_f32_e32 v101, v45
	v_pk_mul_f32 v[42:43], v[42:43], v[102:103]
	ds_read_u16 v102, v68 offset:9248
	ds_read_u16 v103, v97 offset:9520
	v_pk_add_f32 v[40:41], v[40:41], 1.0 op_sel_hi:[1,0]
	v_pk_fma_f32 v[44:45], v[100:101], v[100:101], 1.0 op_sel_hi:[1,1,0] neg_lo:[1,0,0] neg_hi:[1,0,0]
	ds_read_u16 v106, v97 offset:8976
	ds_read_u16 v107, v68 offset:8704
	v_rcp_f32_e32 v40, v40
	v_rcp_f32_e32 v41, v41
	v_sqrt_f32_e32 v44, v44
	v_sqrt_f32_e32 v45, v45
	s_waitcnt lgkmcnt(3)
	v_lshlrev_b32_e32 v102, 16, v102
	s_waitcnt lgkmcnt(2)
	v_lshlrev_b32_e32 v103, 16, v103
	v_pk_mul_f32 v[104:105], v[42:43], v[102:103]
	v_pk_mul_f32 v[40:41], v[40:41], v[44:45]
	s_waitcnt lgkmcnt(0)
; DI float bf2f(unsigned short b) { return __uint_as_float(((unsigned)b) << 16); }
; DI float ex2(float x) { return __builtin_amdgcn_exp2f(x); }
; DI float rcpf_(float x) { return __builtin_amdgcn_rcpf(x); }
; DI void lru_tile(const Params& p, unsigned char* shm, int c, int nb, const LruPar par) {
;     ...
;         for (int rt = 0; rt < 8; ++rt) {
;             float av[4], bv[4];
; #pragma unroll
;             for (int jp = 0; jp < 2; ++jp) {
;                 const f32x2 xr = {acc[0][rt][2 * jp], acc[0][rt][2 * jp + 1]}, xi = {acc[1][rt][2 * jp], acc[1][rt][2 * jp + 1]};
;                 f32x2 er = xr * nl2 + nbr2, ei = xi * nl2 + nbi2;
;                 er = (f32x2){ex2(er[0]), ex2(er[1])} + one2; ei = (f32x2){ex2(ei[0]), ex2(ei[1])} + one2;
;                 const f32x2 r = {rcpf_(er[0]), rcpf_(er[1])}, ig = {rcpf_(ei[0]), rcpf_(ei[1])};
;                 const f32x2 la = r * cd2;
;                 const f32x2 a = {ex2(la[0]), ex2(la[1])};
;                 const f32x2 om = one2 - a * a;
;                 const f32x2 sc = {__builtin_amdgcn_sqrtf(om[0]), __builtin_amdgcn_sqrtf(om[1])};
;                 const f32x2 u2 = {bf2f(UB[(rt * 16 + 4 * q + 2 * jp) * LDU + chl]), bf2f(UB[(rt * 16 + 4 * q + 2 * jp + 1) * LDU + chl])};
;                 const f32x2 b2 = sc * ig * u2;
;                 av[2 * jp] = a[0]; av[2 * jp + 1] = a[1]; bv[2 * jp] = b2[0]; bv[2 * jp + 1] = b2[1];
;             }
;             float h = 0.f, P = 1.f;
;             if (d == 0) {
; #pragma unroll
;                 for (int j = 0; j < 4; ++j) { h = fmaf(av[j], h, bv[j]); P *= av[j]; hl[rt][j] = h; pc[rt][j] = P; }
;             } else {
; #pragma unroll
;                 for (int j = 3; j >= 0; --j) { h = fmaf(av[j], h, bv[j]); P *= av[j]; hl[rt][j] = h; pc[rt][j] = P; }
;             }
;             AG[(rt * 4 + q) * 16 + col] = (f32x2){P, h};
;             __builtin_amdgcn_sched_barrier(0);
	v_lshlrev_b32_e32 v42, 16, v107
	v_lshlrev_b32_e32 v43, 16, v106
	v_pk_mul_f32 v[102:103], v[40:41], v[42:43]
	s_nop 0
	v_fma_f32 v102, 0, v100, v102
	v_fmac_f32_e32 v103, v101, v102
	v_mul_f32_e32 v101, v100, v101
	v_fma_f32 v106, v46, v103, v104
	v_mul_f32_e32 v108, v46, v101
	v_fmac_f32_e32 v105, v47, v106
	v_mul_f32_e32 v104, v47, v108
	ds_write_b64 v61, v[104:105] offset:1024
	v_pk_fma_f32 v[38:39], v[38:39], s[50:51], v[82:83] op_sel_hi:[1,0,0] neg_lo:[1,0,0] neg_hi:[1,0,0]
	v_pk_fma_f32 v[36:37], v[36:37], s[50:51], v[82:83] op_sel_hi:[1,0,0] neg_lo:[1,0,0] neg_hi:[1,0,0]
	v_exp_f32_e32 v38, v38
	v_exp_f32_e32 v39, v39
	v_exp_f32_e32 v36, v36
	v_exp_f32_e32 v37, v37
	v_pk_fma_f32 v[34:35], v[34:35], s[50:51], v[86:87] op_sel_hi:[1,0,0] neg_lo:[1,0,0] neg_hi:[1,0,0]
	v_pk_add_f32 v[38:39], v[38:39], 1.0 op_sel_hi:[1,0]
	v_exp_f32_e32 v34, v34
	v_rcp_f32_e32 v38, v38
	v_rcp_f32_e32 v39, v39
	v_pk_add_f32 v[36:37], v[36:37], 1.0 op_sel_hi:[1,0]
	v_exp_f32_e32 v35, v35
	v_rcp_f32_e32 v36, v36
	v_pk_mul_f32 v[38:39], v[92:93], v[38:39] op_sel_hi:[0,1]
	v_exp_f32_e32 v38, v38
	v_exp_f32_e32 v39, v39
	v_rcp_f32_e32 v37, v37
	v_pk_add_f32 v[34:35], v[34:35], 1.0 op_sel_hi:[1,0]
	v_pk_fma_f32 v[32:33], v[32:33], s[50:51], v[86:87] op_sel_hi:[1,0,0] neg_lo:[1,0,0] neg_hi:[1,0,0]
	v_pk_fma_f32 v[40:41], v[38:39], v[38:39], 1.0 op_sel_hi:[1,1,0] neg_lo:[1,0,0] neg_hi:[1,0,0]
	v_rcp_f32_e32 v34, v34
	v_rcp_f32_e32 v35, v35
	v_sqrt_f32_e32 v40, v40
	v_sqrt_f32_e32 v41, v41
	v_pk_mul_f32 v[36:37], v[92:93], v[36:37] op_sel_hi:[0,1]
	v_exp_f32_e32 v110, v36
	v_exp_f32_e32 v32, v32
	v_exp_f32_e32 v33, v33
	v_exp_f32_e32 v111, v37
	v_pk_mul_f32 v[34:35], v[34:35], v[40:41]
	ds_read_u16 v40, v68 offset:13600
	ds_read_u16 v41, v97 offset:13872
	v_pk_add_f32 v[32:33], v[32:33], 1.0 op_sel_hi:[1,0]
	v_pk_fma_f32 v[36:37], v[110:111], v[110:111], 1.0 op_sel_hi:[1,1,0] neg_lo:[1,0,0] neg_hi:[1,0,0]
	ds_read_u16 v42, v97 offset:13328
	ds_read_u16 v43, v68 offset:13056
	v_rcp_f32_e32 v32, v32
	v_rcp_f32_e32 v33, v33
	v_sqrt_f32_e32 v36, v36
	v_sqrt_f32_e32 v37, v37
	s_waitcnt lgkmcnt(3)
	v_lshlrev_b32_e32 v40, 16, v40
	s_waitcnt lgkmcnt(2)
	v_lshlrev_b32_e32 v41, 16, v41
	v_pk_mul_f32 v[114:115], v[34:35], v[40:41]
	v_pk_mul_f32 v[32:33], v[32:33], v[36:37]
	s_waitcnt lgkmcnt(0)
	v_lshlrev_b32_e32 v34, 16, v43
	v_lshlrev_b32_e32 v35, 16, v42
	v_pk_mul_f32 v[112:113], v[32:33], v[34:35]
	s_nop 0
	v_fma_f32 v112, 0, v110, v112
	v_fmac_f32_e32 v113, v111, v112
	v_mul_f32_e32 v111, v110, v111
	v_fma_f32 v116, v38, v113, v114
	v_mul_f32_e32 v118, v38, v111
	v_fmac_f32_e32 v115, v39, v116
	v_mul_f32_e32 v114, v39, v118
	ds_write_b64 v61, v[114:115] offset:1536
	v_pk_fma_f32 v[30:31], v[30:31], s[50:51], v[82:83] op_sel_hi:[1,0,0] neg_lo:[1,0,0] neg_hi:[1,0,0]
	v_pk_fma_f32 v[28:29], v[28:29], s[50:51], v[82:83] op_sel_hi:[1,0,0] neg_lo:[1,0,0] neg_hi:[1,0,0]
	v_exp_f32_e32 v30, v30
	v_exp_f32_e32 v31, v31
	v_exp_f32_e32 v28, v28
	v_exp_f32_e32 v29, v29
	v_pk_fma_f32 v[26:27], v[26:27], s[50:51], v[86:87] op_sel_hi:[1,0,0] neg_lo:[1,0,0] neg_hi:[1,0,0]
	v_pk_add_f32 v[30:31], v[30:31], 1.0 op_sel_hi:[1,0]
	v_exp_f32_e32 v26, v26
	v_rcp_f32_e32 v30, v30
	v_rcp_f32_e32 v31, v31
	v_pk_add_f32 v[28:29], v[28:29], 1.0 op_sel_hi:[1,0]
	v_exp_f32_e32 v27, v27
	v_rcp_f32_e32 v28, v28
	v_pk_mul_f32 v[30:31], v[92:93], v[30:31] op_sel_hi:[0,1]
	v_exp_f32_e32 v30, v30
	v_exp_f32_e32 v31, v31
	v_rcp_f32_e32 v29, v29
	v_pk_add_f32 v[26:27], v[26:27], 1.0 op_sel_hi:[1,0]
	v_pk_fma_f32 v[24:25], v[24:25], s[50:51], v[86:87] op_sel_hi:[1,0,0] neg_lo:[1,0,0] neg_hi:[1,0,0]
	v_pk_fma_f32 v[32:33], v[30:31], v[30:31], 1.0 op_sel_hi:[1,1,0] neg_lo:[1,0,0] neg_hi:[1,0,0]
	v_rcp_f32_e32 v26, v26
	v_rcp_f32_e32 v27, v27
	v_sqrt_f32_e32 v32, v32
	v_sqrt_f32_e32 v33, v33
	v_pk_mul_f32 v[28:29], v[92:93], v[28:29] op_sel_hi:[0,1]
	v_exp_f32_e32 v120, v28
	v_exp_f32_e32 v24, v24
	v_exp_f32_e32 v25, v25
	v_exp_f32_e32 v121, v29
	v_pk_mul_f32 v[26:27], v[26:27], v[32:33]
	ds_read_u16 v32, v68 offset:17952
	ds_read_u16 v33, v97 offset:18224
	v_pk_add_f32 v[24:25], v[24:25], 1.0 op_sel_hi:[1,0]
	v_pk_fma_f32 v[28:29], v[120:121], v[120:121], 1.0 op_sel_hi:[1,1,0] neg_lo:[1,0,0] neg_hi:[1,0,0]
	ds_read_u16 v34, v97 offset:17680
	ds_read_u16 v35, v68 offset:17408
	v_rcp_f32_e32 v24, v24
	v_rcp_f32_e32 v25, v25
	v_sqrt_f32_e32 v28, v28
	v_sqrt_f32_e32 v29, v29
	s_waitcnt lgkmcnt(3)
	v_lshlrev_b32_e32 v32, 16, v32
	s_waitcnt lgkmcnt(2)
	v_lshlrev_b32_e32 v33, 16, v33
	v_pk_mul_f32 v[124:125], v[26:27], v[32:33]
	v_pk_mul_f32 v[24:25], v[24:25], v[28:29]
	s_waitcnt lgkmcnt(0)
; DI float bf2f(unsigned short b) { return __uint_as_float(((unsigned)b) << 16); }
; DI float ex2(float x) { return __builtin_amdgcn_exp2f(x); }
; DI float rcpf_(float x) { return __builtin_amdgcn_rcpf(x); }
; DI void lru_tile(const Params& p, unsigned char* shm, int c, int nb, const LruPar par) {
;     ...
;         for (int rt = 0; rt < 8; ++rt) {
;             float av[4], bv[4];
; #pragma unroll
;             for (int jp = 0; jp < 2; ++jp) {
;                 const f32x2 xr = {acc[0][rt][2 * jp], acc[0][rt][2 * jp + 1]}, xi = {acc[1][rt][2 * jp], acc[1][rt][2 * jp + 1]};
;                 f32x2 er = xr * nl2 + nbr2, ei = xi * nl2 + nbi2;
;                 er = (f32x2){ex2(er[0]), ex2(er[1])} + one2; ei = (f32x2){ex2(ei[0]), ex2(ei[1])} + one2;
;                 const f32x2 r = {rcpf_(er[0]), rcpf_(er[1])}, ig = {rcpf_(ei[0]), rcpf_(ei[1])};
;                 const f32x2 la = r * cd2;
;                 const f32x2 a = {ex2(la[0]), ex2(la[1])};
;                 const f32x2 om = one2 - a * a;
;                 const f32x2 sc = {__builtin_amdgcn_sqrtf(om[0]), __builtin_amdgcn_sqrtf(om[1])};
;                 const f32x2 u2 = {bf2f(UB[(rt * 16 + 4 * q + 2 * jp) * LDU + chl]), bf2f(UB[(rt * 16 + 4 * q + 2 * jp + 1) * LDU + chl])};
;                 const f32x2 b2 = sc * ig * u2;
;                 av[2 * jp] = a[0]; av[2 * jp + 1] = a[1]; bv[2 * jp] = b2[0]; bv[2 * jp + 1] = b2[1];
;             }
;             float h = 0.f, P = 1.f;
;             if (d == 0) {
; #pragma unroll
;                 for (int j = 0; j < 4; ++j) { h = fmaf(av[j], h, bv[j]); P *= av[j]; hl[rt][j] = h; pc[rt][j] = P; }
;             } else {
; #pragma unroll
;                 for (int j = 3; j >= 0; --j) { h = fmaf(av[j], h, bv[j]); P *= av[j]; hl[rt][j] = h; pc[rt][j] = P; }
;             }
;             AG[(rt * 4 + q) * 16 + col] = (f32x2){P, h};
;             __builtin_amdgcn_sched_barrier(0);
	v_lshlrev_b32_e32 v26, 16, v35
	v_lshlrev_b32_e32 v27, 16, v34
	v_pk_mul_f32 v[122:123], v[24:25], v[26:27]
	s_nop 0
	v_fma_f32 v122, 0, v120, v122
	v_fmac_f32_e32 v123, v121, v122
	v_mul_f32_e32 v121, v120, v121
	v_fma_f32 v126, v30, v123, v124
	v_mul_f32_e32 v128, v30, v121
	v_fmac_f32_e32 v125, v31, v126
	v_mul_f32_e32 v124, v31, v128
	ds_write_b64 v61, v[124:125] offset:2048
	v_pk_fma_f32 v[22:23], v[22:23], s[50:51], v[82:83] op_sel_hi:[1,0,0] neg_lo:[1,0,0] neg_hi:[1,0,0]
	v_pk_fma_f32 v[20:21], v[20:21], s[50:51], v[82:83] op_sel_hi:[1,0,0] neg_lo:[1,0,0] neg_hi:[1,0,0]
	v_exp_f32_e32 v22, v22
	v_exp_f32_e32 v23, v23
	v_exp_f32_e32 v20, v20
	v_exp_f32_e32 v21, v21
	v_pk_fma_f32 v[18:19], v[18:19], s[50:51], v[86:87] op_sel_hi:[1,0,0] neg_lo:[1,0,0] neg_hi:[1,0,0]
	v_pk_add_f32 v[22:23], v[22:23], 1.0 op_sel_hi:[1,0]
	v_exp_f32_e32 v18, v18
	v_rcp_f32_e32 v22, v22
	v_rcp_f32_e32 v23, v23
	v_pk_add_f32 v[20:21], v[20:21], 1.0 op_sel_hi:[1,0]
	v_exp_f32_e32 v19, v19
	v_rcp_f32_e32 v20, v20
	v_pk_mul_f32 v[22:23], v[92:93], v[22:23] op_sel_hi:[0,1]
	v_exp_f32_e32 v22, v22
	v_exp_f32_e32 v23, v23
	v_rcp_f32_e32 v21, v21
	v_pk_add_f32 v[18:19], v[18:19], 1.0 op_sel_hi:[1,0]
	v_pk_fma_f32 v[16:17], v[16:17], s[50:51], v[86:87] op_sel_hi:[1,0,0] neg_lo:[1,0,0] neg_hi:[1,0,0]
	v_pk_fma_f32 v[24:25], v[22:23], v[22:23], 1.0 op_sel_hi:[1,1,0] neg_lo:[1,0,0] neg_hi:[1,0,0]
	v_rcp_f32_e32 v18, v18
	v_rcp_f32_e32 v19, v19
	v_sqrt_f32_e32 v24, v24
	v_sqrt_f32_e32 v25, v25
	v_pk_mul_f32 v[20:21], v[92:93], v[20:21] op_sel_hi:[0,1]
	v_exp_f32_e32 v130, v20
	v_exp_f32_e32 v16, v16
	v_exp_f32_e32 v17, v17
	v_exp_f32_e32 v131, v21
	v_pk_mul_f32 v[18:19], v[18:19], v[24:25]
	ds_read_u16 v24, v68 offset:22304
	ds_read_u16 v25, v97 offset:22576
	v_pk_add_f32 v[16:17], v[16:17], 1.0 op_sel_hi:[1,0]
	v_pk_fma_f32 v[20:21], v[130:131], v[130:131], 1.0 op_sel_hi:[1,1,0] neg_lo:[1,0,0] neg_hi:[1,0,0]
	ds_read_u16 v26, v97 offset:22032
	ds_read_u16 v27, v68 offset:21760
	v_rcp_f32_e32 v16, v16
	v_rcp_f32_e32 v17, v17
	v_sqrt_f32_e32 v20, v20
	v_sqrt_f32_e32 v21, v21
	s_waitcnt lgkmcnt(3)
	v_lshlrev_b32_e32 v24, 16, v24
	s_waitcnt lgkmcnt(2)
	v_lshlrev_b32_e32 v25, 16, v25
	v_pk_mul_f32 v[134:135], v[18:19], v[24:25]
	v_pk_mul_f32 v[16:17], v[16:17], v[20:21]
	s_waitcnt lgkmcnt(0)
	v_lshlrev_b32_e32 v18, 16, v27
	v_lshlrev_b32_e32 v19, 16, v26
	v_pk_mul_f32 v[132:133], v[16:17], v[18:19]
	s_nop 0
	v_fma_f32 v132, 0, v130, v132
	v_fmac_f32_e32 v133, v131, v132
	v_mul_f32_e32 v131, v130, v131
	v_fma_f32 v136, v22, v133, v134
	v_mul_f32_e32 v138, v22, v131
	v_fmac_f32_e32 v135, v23, v136
	v_mul_f32_e32 v134, v23, v138
	ds_write_b64 v61, v[134:135] offset:2560
	v_pk_fma_f32 v[14:15], v[14:15], s[50:51], v[82:83] op_sel_hi:[1,0,0] neg_lo:[1,0,0] neg_hi:[1,0,0]
	v_pk_fma_f32 v[12:13], v[12:13], s[50:51], v[82:83] op_sel_hi:[1,0,0] neg_lo:[1,0,0] neg_hi:[1,0,0]
	v_exp_f32_e32 v14, v14
	v_exp_f32_e32 v15, v15
	v_exp_f32_e32 v12, v12
	v_exp_f32_e32 v13, v13
	v_pk_fma_f32 v[10:11], v[10:11], s[50:51], v[86:87] op_sel_hi:[1,0,0] neg_lo:[1,0,0] neg_hi:[1,0,0]
	v_pk_add_f32 v[14:15], v[14:15], 1.0 op_sel_hi:[1,0]
	v_exp_f32_e32 v10, v10
	v_rcp_f32_e32 v14, v14
	v_rcp_f32_e32 v15, v15
	v_pk_add_f32 v[12:13], v[12:13], 1.0 op_sel_hi:[1,0]
	v_exp_f32_e32 v11, v11
	v_rcp_f32_e32 v12, v12
	v_pk_mul_f32 v[14:15], v[92:93], v[14:15] op_sel_hi:[0,1]
	v_exp_f32_e32 v14, v14
	v_exp_f32_e32 v15, v15
	v_rcp_f32_e32 v13, v13
	v_pk_add_f32 v[10:11], v[10:11], 1.0 op_sel_hi:[1,0]
	v_pk_fma_f32 v[8:9], v[8:9], s[50:51], v[86:87] op_sel_hi:[1,0,0] neg_lo:[1,0,0] neg_hi:[1,0,0]
	v_pk_fma_f32 v[16:17], v[14:15], v[14:15], 1.0 op_sel_hi:[1,1,0] neg_lo:[1,0,0] neg_hi:[1,0,0]
	v_rcp_f32_e32 v10, v10
	v_rcp_f32_e32 v11, v11
	v_sqrt_f32_e32 v16, v16
	v_sqrt_f32_e32 v17, v17
	v_pk_mul_f32 v[12:13], v[92:93], v[12:13] op_sel_hi:[0,1]
	v_exp_f32_e32 v140, v12
	v_exp_f32_e32 v8, v8
	v_exp_f32_e32 v9, v9
	v_exp_f32_e32 v141, v13
	v_pk_mul_f32 v[10:11], v[10:11], v[16:17]
	ds_read_u16 v16, v68 offset:26656
	ds_read_u16 v17, v97 offset:26928
	v_pk_add_f32 v[8:9], v[8:9], 1.0 op_sel_hi:[1,0]
	v_pk_fma_f32 v[12:13], v[140:141], v[140:141], 1.0 op_sel_hi:[1,1,0] neg_lo:[1,0,0] neg_hi:[1,0,0]
	ds_read_u16 v18, v97 offset:26384
	ds_read_u16 v19, v68 offset:26112
	v_rcp_f32_e32 v8, v8
	v_rcp_f32_e32 v9, v9
	v_sqrt_f32_e32 v12, v12
	v_sqrt_f32_e32 v13, v13
	s_waitcnt lgkmcnt(3)
	v_lshlrev_b32_e32 v16, 16, v16
	s_waitcnt lgkmcnt(2)
	v_lshlrev_b32_e32 v17, 16, v17
	v_pk_mul_f32 v[144:145], v[10:11], v[16:17]
	v_pk_mul_f32 v[8:9], v[8:9], v[12:13]
	s_waitcnt lgkmcnt(0)
	v_lshlrev_b32_e32 v10, 16, v19
	v_lshlrev_b32_e32 v11, 16, v18
	v_pk_mul_f32 v[142:143], v[8:9], v[10:11]
	s_nop 0
	v_fma_f32 v142, 0, v140, v142
	v_fmac_f32_e32 v143, v141, v142
	v_mul_f32_e32 v141, v140, v141
	v_fma_f32 v146, v14, v143, v144
	v_mul_f32_e32 v148, v14, v141
	v_fmac_f32_e32 v145, v15, v146
	v_mul_f32_e32 v144, v15, v148
	ds_write_b64 v61, v[144:145] offset:3072
	v_pk_fma_f32 v[6:7], v[6:7], s[50:51], v[82:83] op_sel_hi:[1,0,0] neg_lo:[1,0,0] neg_hi:[1,0,0]
	v_pk_fma_f32 v[4:5], v[4:5], s[50:51], v[82:83] op_sel_hi:[1,0,0] neg_lo:[1,0,0] neg_hi:[1,0,0]
	v_exp_f32_e32 v6, v6
	v_exp_f32_e32 v7, v7
	v_exp_f32_e32 v4, v4
	v_exp_f32_e32 v5, v5
	v_pk_fma_f32 v[2:3], v[2:3], s[50:51], v[86:87] op_sel_hi:[1,0,0] neg_lo:[1,0,0] neg_hi:[1,0,0]
	v_pk_add_f32 v[6:7], v[6:7], 1.0 op_sel_hi:[1,0]
	v_exp_f32_e32 v2, v2
	v_rcp_f32_e32 v6, v6
	v_rcp_f32_e32 v7, v7
	v_pk_add_f32 v[4:5], v[4:5], 1.0 op_sel_hi:[1,0]
	v_exp_f32_e32 v3, v3
	v_rcp_f32_e32 v4, v4
	v_pk_mul_f32 v[6:7], v[92:93], v[6:7] op_sel_hi:[0,1]
	v_exp_f32_e32 v6, v6
	v_exp_f32_e32 v7, v7
	v_rcp_f32_e32 v5, v5
	v_pk_add_f32 v[2:3], v[2:3], 1.0 op_sel_hi:[1,0]
	v_pk_fma_f32 v[0:1], v[0:1], s[50:51], v[86:87] op_sel_hi:[1,0,0] neg_lo:[1,0,0] neg_hi:[1,0,0]
	v_pk_fma_f32 v[8:9], v[6:7], v[6:7], 1.0 op_sel_hi:[1,1,0] neg_lo:[1,0,0] neg_hi:[1,0,0]
	v_rcp_f32_e32 v2, v2
	v_rcp_f32_e32 v3, v3
	v_sqrt_f32_e32 v8, v8
	v_sqrt_f32_e32 v9, v9
	v_pk_mul_f32 v[4:5], v[92:93], v[4:5] op_sel_hi:[0,1]
	v_exp_f32_e32 v150, v4
	v_exp_f32_e32 v0, v0
	v_exp_f32_e32 v1, v1
	v_exp_f32_e32 v151, v5
	v_pk_mul_f32 v[2:3], v[2:3], v[8:9]
	ds_read_u16 v8, v68 offset:31008
	ds_read_u16 v9, v97 offset:31280
	v_pk_add_f32 v[0:1], v[0:1], 1.0 op_sel_hi:[1,0]
	v_pk_fma_f32 v[4:5], v[150:151], v[150:151], 1.0 op_sel_hi:[1,1,0] neg_lo:[1,0,0] neg_hi:[1,0,0]
	ds_read_u16 v10, v97 offset:30736
	ds_read_u16 v11, v68 offset:30464
	v_rcp_f32_e32 v0, v0
	v_rcp_f32_e32 v1, v1
	v_sqrt_f32_e32 v4, v4
	v_sqrt_f32_e32 v5, v5
	s_waitcnt lgkmcnt(3)
; DI void lru_tile(const Params& p, unsigned char* shm, int c, int nb, const LruPar par) {
;     ...
;                 for (int j = 0; j < 4; ++j) { h = fmaf(av[j], h, bv[j]); P *= av[j]; hl[rt][j] = h; pc[rt][j] = P; }
;             } else {
; #pragma unroll
;                 for (int j = 3; j >= 0; --j) { h = fmaf(av[j], h, bv[j]); P *= av[j]; hl[rt][j] = h; pc[rt][j] = P; }
;             }
;             AG[(rt * 4 + q) * 16 + col] = (f32x2){P, h};
;             __builtin_amdgcn_sched_barrier(0);
;         }
;         asm volatile("s_waitcnt lgkmcnt(0)" ::: "memory");
;         float carry[8], pref[8]; float cin = 0.f, pa = 1.f;
; #pragma unroll
;         for (int gi = 0; gi < 32; ++gi) {
;             const int G = d == 0 ? gi : 31 - gi; const int rt = G >> 2, qq = G & 3;
;             const f32x2 ah = AG[G * 16 + col];
;             if (qq == q) { carry[rt] = cin; pref[rt] = pa; }
;             cin = fmaf(ah[0], cin, ah[1]); pa *= ah[0];
;         }
;         if (q == 0) AGG[((size_t)d * 128 + c) * 2048 + chg] = (f32x2){pa, cin};
	v_lshlrev_b32_e32 v8, 16, v8
	s_waitcnt lgkmcnt(2)
	v_lshlrev_b32_e32 v9, 16, v9
	v_pk_mul_f32 v[154:155], v[2:3], v[8:9]
	v_pk_mul_f32 v[0:1], v[0:1], v[4:5]
	s_waitcnt lgkmcnt(0)
	v_lshlrev_b32_e32 v2, 16, v11
	v_lshlrev_b32_e32 v3, 16, v10
	v_pk_mul_f32 v[152:153], v[0:1], v[2:3]
	s_nop 0
	v_fma_f32 v152, 0, v150, v152
	v_fmac_f32_e32 v153, v151, v152
	v_mul_f32_e32 v151, v150, v151
	v_fma_f32 v156, v6, v153, v154
	v_mul_f32_e32 v158, v6, v151
	v_fmac_f32_e32 v155, v7, v156
	v_mul_f32_e32 v154, v7, v158
	ds_write_b64 v61, v[154:155] offset:3584
	s_waitcnt lgkmcnt(0)
	ds_read2_b64 v[0:3], v59 offset1:16
	v_cndmask_b32_e64 v4, v180, 1.0, s[10:11]
	v_cmp_eq_u32_e64 s[4:5], 1, v99
	v_cmp_eq_u32_e64 s[6:7], 2, v99
	v_cmp_eq_u32_e64 s[8:9], 3, v99
	s_waitcnt lgkmcnt(0)
	v_cndmask_b32_e64 v8, v4, v0, s[4:5]
	ds_read2_b64 v[4:7], v59 offset0:32 offset1:48
	v_fma_f32 v119, 0, v0, v1
	v_cndmask_b32_e64 v9, 1.0, v0, s[4:5]
	v_fma_f32 v127, v2, v119, v3
	v_pk_mul_f32 v[0:1], v[0:1], v[2:3]
	s_waitcnt lgkmcnt(0)
	v_fma_f32 v129, v4, v127, v5
	v_cndmask_b32_e64 v2, v8, v0, s[6:7]
	v_pk_mul_f32 v[4:5], v[0:1], v[4:5]
	v_cndmask_b32_e64 v8, v9, v0, s[6:7]
	v_cndmask_b32_e64 v178, v2, v4, s[8:9]
	ds_read2_b64 v[0:3], v59 offset0:64 offset1:80
	v_cndmask_b32_e64 v181, v8, v4, s[8:9]
	v_fma_f32 v137, v6, v129, v7
	v_pk_mul_f32 v[4:5], v[4:5], v[6:7]
	s_waitcnt lgkmcnt(0)
	v_fma_f32 v139, v0, v137, v1
	v_cndmask_b32_e64 v8, v162, v4, s[10:11]
	v_pk_mul_f32 v[0:1], v[4:5], v[0:1]
	ds_read2_b64 v[4:7], v59 offset0:96 offset1:112
	v_cndmask_b32_e64 v8, v8, v0, s[4:5]
	v_fma_f32 v147, v2, v139, v3
	v_pk_mul_f32 v[0:1], v[0:1], v[2:3]
	ds_read_b64 v[162:163], v59 offset:3840
	v_cndmask_b32_e64 v8, v8, v0, s[6:7]
	s_waitcnt lgkmcnt(1)
	v_fma_f32 v149, v4, v147, v5
	v_pk_mul_f32 v[4:5], v[0:1], v[4:5]
	ds_read2_b64 v[0:3], v59 offset0:128 offset1:144
	v_cndmask_b32_e64 v99, v8, v4, s[8:9]
	v_fma_f32 v157, v6, v149, v7
	v_pk_mul_f32 v[4:5], v[4:5], v[6:7]
	s_waitcnt lgkmcnt(0)
	v_fma_f32 v159, v0, v157, v1
	v_cndmask_b32_e64 v8, v91, v4, s[10:11]
	v_pk_mul_f32 v[0:1], v[4:5], v[0:1]
	ds_read2_b64 v[4:7], v59 offset0:160 offset1:176
	v_cndmask_b32_e64 v8, v8, v0, s[4:5]
	v_fma_f32 v183, v2, v159, v3
	v_pk_mul_f32 v[0:1], v[0:1], v[2:3]
	s_waitcnt lgkmcnt(0)
	v_fma_f32 v184, v4, v183, v5
	v_cndmask_b32_e64 v8, v8, v0, s[6:7]
	v_pk_mul_f32 v[4:5], v[0:1], v[4:5]
	ds_read2_b64 v[0:3], v59 offset0:192 offset1:208
	v_cndmask_b32_e64 v107, v8, v4, s[8:9]
	v_fma_f32 v185, v6, v184, v7
	v_pk_mul_f32 v[4:5], v[4:5], v[6:7]
	s_waitcnt lgkmcnt(0)
	v_fma_f32 v186, v0, v185, v1
	v_cndmask_b32_e64 v8, v89, v4, s[10:11]
	v_pk_mul_f32 v[0:1], v[4:5], v[0:1]
	ds_read2_b64 v[4:7], v59 offset0:224 offset1:240
	v_cndmask_b32_e64 v8, v8, v0, s[4:5]
	v_fma_f32 v187, v2, v186, v3
	v_pk_mul_f32 v[0:1], v[0:1], v[2:3]
	v_add_u32_e32 v89, 0x800, v59
	v_cndmask_b32_e64 v8, v8, v0, s[6:7]
	s_waitcnt lgkmcnt(0)
	v_fma_f32 v188, v4, v187, v5
	v_pk_mul_f32 v[4:5], v[0:1], v[4:5]
	ds_read2_b64 v[0:3], v89 offset1:16
	v_cndmask_b32_e64 v109, v8, v4, s[8:9]
	v_fma_f32 v189, v6, v188, v7
	v_pk_mul_f32 v[4:5], v[4:5], v[6:7]
	s_waitcnt lgkmcnt(0)
	v_fma_f32 v190, v0, v189, v1
	v_cndmask_b32_e64 v8, v85, v4, s[10:11]
	v_pk_mul_f32 v[0:1], v[4:5], v[0:1]
	ds_read2_b64 v[4:7], v89 offset0:32 offset1:48
	v_cndmask_b32_e64 v8, v8, v0, s[4:5]
	v_fma_f32 v192, v2, v190, v3
	v_pk_mul_f32 v[0:1], v[0:1], v[2:3]
	s_waitcnt lgkmcnt(0)
	v_fma_f32 v193, v4, v192, v5
	v_cndmask_b32_e64 v8, v8, v0, s[6:7]
	v_pk_mul_f32 v[4:5], v[0:1], v[4:5]
	ds_read2_b64 v[0:3], v89 offset0:64 offset1:80
	v_cndmask_b32_e64 v117, v8, v4, s[8:9]
	v_fma_f32 v194, v6, v193, v7
	v_pk_mul_f32 v[4:5], v[4:5], v[6:7]
	s_waitcnt lgkmcnt(0)
	v_fma_f32 v195, v0, v194, v1
	v_cndmask_b32_e64 v8, v81, v4, s[10:11]
	v_pk_mul_f32 v[0:1], v[4:5], v[0:1]
	ds_read2_b64 v[4:7], v89 offset0:96 offset1:112
	v_cndmask_b32_e64 v8, v8, v0, s[4:5]
	v_fma_f32 v196, v2, v195, v3
	v_pk_mul_f32 v[0:1], v[0:1], v[2:3]
	s_waitcnt lgkmcnt(0)
	v_fma_f32 v197, v4, v196, v5
	v_cndmask_b32_e64 v8, v8, v0, s[6:7]
	v_pk_mul_f32 v[4:5], v[0:1], v[4:5]
	ds_read2_b64 v[0:3], v89 offset0:128 offset1:144
	v_cndmask_b32_e64 v182, v8, v4, s[8:9]
	v_fma_f32 v198, v6, v197, v7
	v_pk_mul_f32 v[4:5], v[4:5], v[6:7]
	s_waitcnt lgkmcnt(0)
	v_fma_f32 v200, v0, v198, v1
	v_cndmask_b32_e64 v8, v79, v4, s[10:11]
	v_pk_mul_f32 v[0:1], v[4:5], v[0:1]
	ds_read2_b64 v[4:7], v89 offset0:160 offset1:176
	v_cndmask_b32_e64 v8, v8, v0, s[4:5]
	v_fma_f32 v201, v2, v200, v3
	v_pk_mul_f32 v[0:1], v[0:1], v[2:3]
	s_waitcnt lgkmcnt(0)
	v_fma_f32 v204, v4, v201, v5
	v_cndmask_b32_e64 v8, v8, v0, s[6:7]
	v_pk_mul_f32 v[4:5], v[0:1], v[4:5]
	ds_read2_b64 v[0:3], v89 offset0:192 offset1:208
	v_cndmask_b32_e64 v191, v8, v4, s[8:9]
	v_fma_f32 v205, v6, v204, v7
	v_pk_mul_f32 v[4:5], v[4:5], v[6:7]
	s_waitcnt lgkmcnt(0)
	v_fma_f32 v206, v0, v205, v1
	v_cndmask_b32_e64 v6, v77, v4, s[10:11]
	v_pk_mul_f32 v[0:1], v[4:5], v[0:1]
	v_fma_f32 v207, v2, v206, v3
	v_cndmask_b32_e64 v4, v6, v0, s[4:5]
	v_pk_mul_f32 v[0:1], v[0:1], v[2:3]
	s_nop 0
	v_cndmask_b32_e64 v77, v4, v0, s[6:7]
	v_pk_mul_f32 v[0:1], v[0:1], v[162:163]
	v_fmac_f32_e32 v163, v162, v207
	v_cndmask_b32_e64 v199, v77, v0, s[8:9]
	s_and_saveexec_b64 s[60:61], s[10:11]
	s_cbranch_execz .LBB0_230
	ds_read_b64 v[2:3], v59 offset:3968
	v_mov_b32_e32 v181, v178
	s_waitcnt lgkmcnt(0)
	v_pk_mul_f32 v[0:1], v[0:1], v[2:3]
	v_fmac_f32_e32 v3, v2, v163
	v_mov_b32_e32 v1, v3
	global_store_dwordx2 v[56:57], v[0:1], off
